# G-phase merge epilogue: P-row loads prefetched 4 steps ahead into dead B-fragment VGPRs, counted vmcnt
# speedup vs baseline: 1.0055x; 1.0055x over previous
; __device__ __forceinline__ float bf2f(unsigned b) { return __uint_as_float(b << 16); }
; __device__ __forceinline__ float sigmoid_fast(float x) { return __builtin_amdgcn_rcpf(1.0f + __expf(-x)); }
;     __device__ __forceinline__ void operator()(EPI_SIG) const {
;         const int row0 = u.pm * 256 + wr * 64 + fr, oc = u.pn * 64 + wc * 16 + 4 * fq;
;         f32x4 bv[4];
; #pragma unroll
;         for (int g = 0; g < 4; ++g) bv[g] = *(const f32x4*)(bg + g * 1024 + oc);
; #pragma unroll
;         for (int ai = 0; ai < 2; ++ai)
; #pragma unroll
;             for (int m = 0; m < 4; ++m) { const int row = row0 + ai * 128 + m * 16; const bf16* prow = P + (((((size_t)u.pm * 16 + u.pn) * 2 + ai) * 4 + m) * 8 + (wr * 4 + wc)) * 1024 + (fq * 16 + fr) * 4;
;                 v2u pw[4];
; #pragma unroll
;                 for (int g = 0; g < 4; ++g) pw[g] = *(const v2u*)(prow + g * 256);
;                 f32x4 t = (f32x4){0.f, 0.f, 0.f, 0.f};
; #pragma unroll
;                 for (int bj = 0; bj < 2; ++bj)
; #pragma unroll
;                     for (int n = 0; n < 2; ++n) { const int g = 2 * bj + n; const f32x4 a = acc[ai][bj][m][n] + bv[g];
;                         t[0] += sigmoid_fast(a[0]) * bf2f(pw[g].x & 0xffffu); t[1] += sigmoid_fast(a[1]) * bf2f(pw[g].x >> 16);
;                         t[2] += sigmoid_fast(a[2]) * bf2f(pw[g].y & 0xffffu); t[3] += sigmoid_fast(a[3]) * bf2f(pw[g].y >> 16); }
.LBB0_1859:
	v_lshl_or_b32 v18, s44, 6, v190
	v_ashrrev_i32_e32 v19, 31, v18
	s_nop 7
	s_nop 7
	s_nop 3
	v_lshl_add_u64 v[2:3], v[18:19], 2, s[8:9]
	global_load_dwordx4 v[14:17], v[2:3], off
	v_add_co_u32_e32 v4, vcc, 0x1000, v2
	s_ashr_i32 s47, s46, 31
	s_nop 0
	v_addc_co_u32_e32 v5, vcc, 0, v3, vcc
	global_load_dwordx4 v[10:13], v[4:5], off
	s_ashr_i32 s45, s44, 31
	v_add_co_u32_e32 v4, vcc, 0x2000, v2
	s_lshl_b64 s[2:3], s[46:47], 21
	s_lshl_b64 s[14:15], s[44:45], 17
	v_addc_co_u32_e32 v5, vcc, 0, v3, vcc
	s_add_u32 s44, s2, s14
	v_add_co_u32_e32 v2, vcc, 0x3000, v2
	s_addc_u32 s45, s3, s15
	s_nop 0
	v_addc_co_u32_e32 v3, vcc, 0, v3, vcc
	v_lshl_add_u64 v[24:25], v[168:169], 0, s[44:45]
	global_load_dwordx4 v[6:9], v[4:5], off
	v_lshl_add_u32 v20, s46, 8, v50
	global_load_dwordx4 v[2:5], v[2:3], off
	s_nop 0
	global_load_dwordx2 v[26:27], v[24:25], off
	global_load_dwordx2 v[28:29], v[24:25], off offset:512
	global_load_dwordx2 v[22:23], v[24:25], off offset:1024
	s_nop 0
	global_load_dwordx2 v[24:25], v[24:25], off offset:1536
	s_add_u32 s14, s44, 0x10000
	s_addc_u32 s15, s45, 0
	v_lshl_add_u64 v[206:207], v[170:171], 0, s[44:45]
	global_load_dwordx2 v[200:201], v[206:207], off
	global_load_dwordx2 v[202:203], v[206:207], off offset:512
	global_load_dwordx2 v[204:205], v[206:207], off offset:1024
	s_nop 0
	global_load_dwordx2 v[206:207], v[206:207], off offset:1536
	v_lshl_add_u64 v[214:215], v[172:173], 0, s[44:45]
	global_load_dwordx2 v[208:209], v[214:215], off
	global_load_dwordx2 v[210:211], v[214:215], off offset:512
	global_load_dwordx2 v[212:213], v[214:215], off offset:1024
	s_nop 0
	global_load_dwordx2 v[214:215], v[214:215], off offset:1536
	v_lshl_add_u64 v[222:223], v[174:175], 0, s[44:45]
	global_load_dwordx2 v[216:217], v[222:223], off
	global_load_dwordx2 v[218:219], v[222:223], off offset:512
	global_load_dwordx2 v[220:221], v[222:223], off offset:1024
	s_nop 0
	global_load_dwordx2 v[222:223], v[222:223], off offset:1536
	v_lshl_add_u64 v[248:249], v[168:169], 0, s[14:15]
	global_load_dwordx2 v[242:243], v[248:249], off
	global_load_dwordx2 v[244:245], v[248:249], off offset:512
	global_load_dwordx2 v[246:247], v[248:249], off offset:1024
	s_nop 0
	global_load_dwordx2 v[248:249], v[248:249], off offset:1536
	s_mov_b32 s2, 0x40000
	s_mov_b32 s58, 0x3f6c835e
	s_mov_b32 s59, 0xbec3ef15
	s_waitcnt vmcnt(16)
	v_pk_add_f32 v[32:33], v[160:161], v[14:15]
	s_nop 0
	v_mul_f32_e32 v21, 0xbfb8aa3b, v32
	v_exp_f32_e32 v21, v21
	v_pk_add_f32 v[30:31], v[162:163], v[16:17]
	v_pk_add_f32 v[144:145], v[144:145], v[14:15]
	v_pk_add_f32 v[128:129], v[128:129], v[14:15]
	v_add_f32_e32 v21, 1.0, v21
	v_rcp_f32_e32 v32, v21
	v_mul_f32_e32 v21, 0xbfb8aa3b, v33
	v_exp_f32_e32 v21, v21
	v_pk_add_f32 v[156:157], v[156:157], v[10:11]
	v_pk_add_f32 v[158:159], v[158:159], v[12:13]
	v_pk_add_f32 v[140:141], v[140:141], v[10:11]
	v_add_f32_e32 v21, 1.0, v21
	v_rcp_f32_e32 v160, v21
	v_mul_f32_e32 v21, 0xbfb8aa3b, v30
	v_exp_f32_e32 v21, v21
	v_pk_add_f32 v[142:143], v[142:143], v[12:13]
	v_pk_add_f32 v[124:125], v[124:125], v[10:11]
	v_pk_add_f32 v[126:127], v[126:127], v[12:13]
	v_add_f32_e32 v21, 1.0, v21
	v_rcp_f32_e32 v30, v21
	v_mul_f32_e32 v21, 0xbfb8aa3b, v31
	v_exp_f32_e32 v21, v21
	v_mul_f32_e32 v31, 0xbfb8aa3b, v157
	v_exp_f32_e32 v31, v31
	s_waitcnt lgkmcnt(0)
	v_lshlrev_b32_e32 v181, 16, v28
	v_add_f32_e32 v21, 1.0, v21
	v_rcp_f32_e32 v162, v21
	v_mul_f32_e32 v21, 0xbfb8aa3b, v156
	v_exp_f32_e32 v21, v21
	v_add_f32_e32 v31, 1.0, v31
	v_lshlrev_b32_e32 v180, 16, v26
	v_rcp_f32_e32 v161, v31
	v_add_f32_e32 v21, 1.0, v21
	v_rcp_f32_e32 v33, v21
	v_pk_add_f32 v[148:149], v[148:149], v[2:3]
	v_pk_add_f32 v[150:151], v[150:151], v[4:5]
	v_pk_add_f32 v[132:133], v[132:133], v[2:3]
	v_pk_mul_f32 v[32:33], v[32:33], v[180:181]
	v_pk_add_f32 v[134:135], v[134:135], v[4:5]
	v_add_f32_e32 v21, 0, v32
	v_add_f32_e32 v21, v21, v33
	v_and_b32_e32 v33, 0xffff0000, v28
	v_and_b32_e32 v32, 0xffff0000, v26
	v_pk_mul_f32 v[32:33], v[160:161], v[32:33]
	v_and_b32_e32 v28, 0xffff0000, v27
	v_add_f32_e32 v26, 0, v32
	v_add_f32_e32 v156, v26, v33
	v_mul_f32_e32 v26, 0xbfb8aa3b, v158
	v_exp_f32_e32 v26, v26
	v_lshlrev_b32_e32 v33, 16, v29
	v_lshlrev_b32_e32 v32, 16, v27
	v_and_b32_e32 v29, 0xffff0000, v29
	v_add_f32_e32 v26, 1.0, v26
	v_rcp_f32_e32 v31, v26
	v_pk_add_f32 v[116:117], v[116:117], v[2:3]
	v_pk_add_f32 v[118:119], v[118:119], v[4:5]
	v_pk_add_f32 v[112:113], v[112:113], v[14:15]
	v_pk_mul_f32 v[30:31], v[30:31], v[32:33]
	v_pk_add_f32 v[108:109], v[108:109], v[10:11]
	v_add_f32_e32 v26, 0, v30
	v_add_f32_e32 v33, v26, v31
	v_mul_f32_e32 v26, 0xbfb8aa3b, v159
	v_exp_f32_e32 v26, v26
	v_pk_add_f32 v[110:111], v[110:111], v[12:13]
	v_pk_add_f32 v[100:101], v[100:101], v[2:3]
	v_pk_add_f32 v[102:103], v[102:103], v[4:5]
	v_add_f32_e32 v26, 1.0, v26
	v_rcp_f32_e32 v163, v26
	v_pk_add_f32 v[92:93], v[92:93], v[10:11]
	v_pk_add_f32 v[94:95], v[94:95], v[12:13]
	v_pk_add_f32 v[84:85], v[84:85], v[2:3]
	v_pk_mul_f32 v[26:27], v[162:163], v[28:29]
	v_pk_add_f32 v[28:29], v[152:153], v[6:7]
	v_add_f32_e32 v26, 0, v26
	v_add_f32_e32 v157, v26, v27
	v_pk_add_f32 v[26:27], v[154:155], v[8:9]
	v_mul_f32_e32 v29, 0xbfb8aa3b, v29
	v_mul_f32_e32 v27, 0xbfb8aa3b, v27
	v_exp_f32_e32 v27, v27
	v_exp_f32_e32 v29, v29
	v_mul_f32_e32 v28, 0xbfb8aa3b, v28
	v_exp_f32_e32 v28, v28
	v_add_f32_e32 v27, 1.0, v27
	v_rcp_f32_e32 v32, v27
	v_mul_f32_e32 v27, 0xbfb8aa3b, v148
	v_exp_f32_e32 v27, v27
	v_add_f32_e32 v29, 1.0, v29
	v_rcp_f32_e32 v30, v29
	v_add_f32_e32 v28, 1.0, v28
	v_add_f32_e32 v27, 1.0, v27
	v_rcp_f32_e32 v29, v27
	v_mul_f32_e32 v27, 0xbfb8aa3b, v149
; __device__ __forceinline__ float bf2f(unsigned b) { return __uint_as_float(b << 16); }
; __device__ __forceinline__ unsigned cvt_pk_bf16(float lo, float hi) { unsigned r; asm volatile("v_cvt_pk_bf16_f32 %0, %1, %2" : "=v"(r) : "v"(lo), "v"(hi)); return r; }
; __device__ __forceinline__ float sigmoid_fast(float x) { return __builtin_amdgcn_rcpf(1.0f + __expf(-x)); }
;     __device__ __forceinline__ void operator()(EPI_SIG) const {
;     ...
;             for (int m = 0; m < 4; ++m) { const int row = row0 + ai * 128 + m * 16; const bf16* prow = P + (((((size_t)u.pm * 16 + u.pn) * 2 + ai) * 4 + m) * 8 + (wr * 4 + wc)) * 1024 + (fq * 16 + fr) * 4;
;                 v2u pw[4];
; #pragma unroll
;                 for (int g = 0; g < 4; ++g) pw[g] = *(const v2u*)(prow + g * 256);
;                 f32x4 t = (f32x4){0.f, 0.f, 0.f, 0.f};
; #pragma unroll
;                 for (int bj = 0; bj < 2; ++bj)
; #pragma unroll
;                     for (int n = 0; n < 2; ++n) { const int g = 2 * bj + n; const f32x4 a = acc[ai][bj][m][n] + bv[g];
;                         t[0] += sigmoid_fast(a[0]) * bf2f(pw[g].x & 0xffffu); t[1] += sigmoid_fast(a[1]) * bf2f(pw[g].x >> 16);
;                         t[2] += sigmoid_fast(a[2]) * bf2f(pw[g].y & 0xffffu); t[3] += sigmoid_fast(a[3]) * bf2f(pw[g].y >> 16); }
;                 v2u w; w.x = cvt_pk_bf16(t[0], t[1]); w.y = cvt_pk_bf16(t[2], t[3]);
;                 *(v2u*)(T + (size_t)row * 1024 + oc) = w; }
	v_exp_f32_e32 v27, v27
	v_rcp_f32_e32 v28, v28
	v_lshlrev_b32_e32 v153, 16, v24
	v_lshlrev_b32_e32 v152, 16, v22
	v_add_f32_e32 v27, 1.0, v27
	v_rcp_f32_e32 v31, v27
	v_pk_mul_f32 v[28:29], v[28:29], v[152:153]
	v_mul_f32_e32 v26, 0xbfb8aa3b, v26
	v_add_f32_e32 v21, v21, v28
	v_add_f32_e32 v21, v21, v29
	v_and_b32_e32 v29, 0xffff0000, v24
	v_and_b32_e32 v28, 0xffff0000, v22
	v_pk_mul_f32 v[28:29], v[30:31], v[28:29]
	v_exp_f32_e32 v26, v26
	v_add_f32_e32 v22, v156, v28
	v_add_f32_e32 v30, v22, v29
	v_mul_f32_e32 v22, 0xbfb8aa3b, v150
	v_exp_f32_e32 v22, v22
	v_add_f32_e32 v26, 1.0, v26
	v_rcp_f32_e32 v26, v26
	v_lshlrev_b32_e32 v29, 16, v25
	v_add_f32_e32 v22, 1.0, v22
	v_rcp_f32_e32 v27, v22
	v_lshlrev_b32_e32 v28, 16, v23
	v_and_b32_e32 v25, 0xffff0000, v25
	v_and_b32_e32 v24, 0xffff0000, v23
	v_pk_mul_f32 v[26:27], v[26:27], v[28:29]
	v_pk_add_f32 v[76:77], v[76:77], v[10:11]
	v_add_f32_e32 v22, v33, v26
	v_add_f32_e32 v26, v22, v27
	v_mul_f32_e32 v22, 0xbfb8aa3b, v151
	v_exp_f32_e32 v22, v22
	v_pk_add_f32 v[78:79], v[78:79], v[12:13]
	v_pk_add_f32 v[68:69], v[68:69], v[2:3]
	v_pk_add_f32 v[60:61], v[60:61], v[10:11]
	v_add_f32_e32 v22, 1.0, v22
	v_rcp_f32_e32 v33, v22
	v_pk_add_f32 v[62:63], v[62:63], v[12:13]
	v_pk_add_f32 v[52:53], v[52:53], v[2:3]
	v_pk_add_f32 v[10:11], v[42:43], v[10:11]
	v_pk_mul_f32 v[22:23], v[32:33], v[24:25]
	v_cvt_pk_bf16_f32 v24, v21, v30
	v_ashrrev_i32_e32 v21, 31, v20
	v_add_f32_e32 v22, v157, v22
	v_add_f32_e32 v22, v22, v23
	v_cvt_pk_bf16_f32 v25, v26, v22
	v_lshlrev_b64 v[22:23], 11, v[20:21]
	v_lshl_add_u64 v[26:27], s[6:7], 0, v[22:23]
	v_lshlrev_b64 v[22:23], 1, v[18:19]
	v_lshl_add_u64 v[18:19], v[26:27], 0, v[22:23]
	global_store_dwordx2 v[18:19], v[24:25], off
	v_mul_f32_e32 v21, 0xbfb8aa3b, v144
	v_exp_f32_e32 v21, v21
	v_pk_add_f32 v[32:33], v[146:147], v[16:17]
	v_mul_f32_e32 v10, 0xbfb8aa3b, v10
	v_exp_f32_e32 v10, v10
	v_add_f32_e32 v21, 1.0, v21
	v_rcp_f32_e32 v144, v21
	v_mul_f32_e32 v21, 0xbfb8aa3b, v145
	v_exp_f32_e32 v21, v21
	v_add_f32_e32 v10, 1.0, v10
	v_pk_add_f32 v[12:13], v[44:45], v[12:13]
	v_pk_add_f32 v[2:3], v[34:35], v[2:3]
	v_add_f32_e32 v21, 1.0, v21
	v_rcp_f32_e32 v146, v21
	v_mul_f32_e32 v21, 0xbfb8aa3b, v32
	v_exp_f32_e32 v21, v21
	v_mul_f32_e32 v2, 0xbfb8aa3b, v2
	v_exp_f32_e32 v2, v2
	v_add_f32_e32 v21, 1.0, v21
	v_rcp_f32_e32 v32, v21
	v_mul_f32_e32 v21, 0xbfb8aa3b, v33
	v_exp_f32_e32 v21, v21
	v_mul_f32_e32 v33, 0xbfb8aa3b, v141
	v_exp_f32_e32 v33, v33
	v_add_f32_e32 v2, 1.0, v2
	v_add_f32_e32 v21, 1.0, v21
	v_rcp_f32_e32 v148, v21
	v_mul_f32_e32 v21, 0xbfb8aa3b, v140
	v_exp_f32_e32 v21, v21
	v_add_f32_e32 v33, 1.0, v33
	v_rcp_f32_e32 v147, v33
	v_add_f32_e32 v21, 1.0, v21
	v_rcp_f32_e32 v145, v21
	s_waitcnt vmcnt(12)
	v_mov_b64_e32 v[28:29], v[200:201]
	v_mov_b64_e32 v[30:31], v[202:203]
	v_mov_b64_e32 v[24:25], v[204:205]
	v_mov_b64_e32 v[26:27], v[206:207]
	v_lshl_add_u64 v[206:207], v[170:171], 0, s[14:15]
	global_load_dwordx2 v[200:201], v[206:207], off
	global_load_dwordx2 v[202:203], v[206:207], off offset:512
	global_load_dwordx2 v[204:205], v[206:207], off offset:1024
	s_nop 0
	global_load_dwordx2 v[206:207], v[206:207], off offset:1536
	v_and_b32_e32 v140, 0xffff0000, v28
	v_and_b32_e32 v141, 0xffff0000, v30
	v_lshlrev_b32_e32 v151, 16, v30
	v_lshlrev_b32_e32 v150, 16, v28
	v_pk_mul_f32 v[140:141], v[146:147], v[140:141]
	v_pk_mul_f32 v[144:145], v[144:145], v[150:151]
	v_add_f32_e32 v28, 0, v140
	v_add_f32_e32 v21, 0, v144
	v_add_f32_e32 v144, v28, v141
	v_mul_f32_e32 v28, 0xbfb8aa3b, v142
	v_exp_f32_e32 v28, v28
	v_lshlrev_b32_e32 v141, 16, v31
	v_lshlrev_b32_e32 v140, 16, v29
	v_and_b32_e32 v31, 0xffff0000, v31
	v_add_f32_e32 v28, 1.0, v28
	v_rcp_f32_e32 v33, v28
	v_and_b32_e32 v30, 0xffff0000, v29
	v_add_f32_e32 v21, v21, v145
	v_pk_mul_f32 v[32:33], v[32:33], v[140:141]
	s_nop 0
	v_add_f32_e32 v28, 0, v32
	v_add_f32_e32 v140, v28, v33
	v_mul_f32_e32 v28, 0xbfb8aa3b, v143
	v_exp_f32_e32 v28, v28
	s_nop 0
	v_add_f32_e32 v28, 1.0, v28
	v_rcp_f32_e32 v149, v28
	s_nop 0
	v_pk_mul_f32 v[28:29], v[148:149], v[30:31]
	s_nop 0
	v_add_f32_e32 v28, 0, v28
	v_add_f32_e32 v141, v28, v29
	v_pk_add_f32 v[28:29], v[138:139], v[8:9]
	v_pk_add_f32 v[30:31], v[136:137], v[6:7]
	v_mul_f32_e32 v29, 0xbfb8aa3b, v29
	v_exp_f32_e32 v29, v29
	v_mul_f32_e32 v31, 0xbfb8aa3b, v31
	v_exp_f32_e32 v31, v31
	v_mul_f32_e32 v30, 0xbfb8aa3b, v30
	v_add_f32_e32 v29, 1.0, v29
	v_rcp_f32_e32 v136, v29
	v_mul_f32_e32 v29, 0xbfb8aa3b, v132
	v_exp_f32_e32 v29, v29
	v_exp_f32_e32 v30, v30
	v_add_f32_e32 v31, 1.0, v31
	v_rcp_f32_e32 v32, v31
	v_add_f32_e32 v29, 1.0, v29
	v_rcp_f32_e32 v31, v29
	v_mul_f32_e32 v29, 0xbfb8aa3b, v133
	v_exp_f32_e32 v29, v29
	v_add_f32_e32 v30, 1.0, v30
	v_rcp_f32_e32 v30, v30
	v_lshlrev_b32_e32 v139, 16, v26
	v_add_f32_e32 v29, 1.0, v29
	v_lshlrev_b32_e32 v138, 16, v24
	v_rcp_f32_e32 v33, v29
	v_pk_mul_f32 v[30:31], v[30:31], v[138:139]
	v_mul_f32_e32 v28, 0xbfb8aa3b, v28
	v_add_f32_e32 v21, v21, v30
	v_add_f32_e32 v21, v21, v31
	v_and_b32_e32 v31, 0xffff0000, v26
	v_and_b32_e32 v30, 0xffff0000, v24
	v_pk_mul_f32 v[30:31], v[32:33], v[30:31]
	v_exp_f32_e32 v28, v28
	v_add_f32_e32 v24, v144, v30
	v_add_f32_e32 v32, v24, v31
	v_mul_f32_e32 v24, 0xbfb8aa3b, v134
	v_exp_f32_e32 v24, v24
	v_add_f32_e32 v28, 1.0, v28
	v_rcp_f32_e32 v28, v28
	v_lshlrev_b32_e32 v31, 16, v27
	v_add_f32_e32 v24, 1.0, v24
	v_rcp_f32_e32 v29, v24
	v_lshlrev_b32_e32 v30, 16, v25
	v_and_b32_e32 v27, 0xffff0000, v27
	v_and_b32_e32 v26, 0xffff0000, v25
	v_pk_mul_f32 v[28:29], v[28:29], v[30:31]
	s_nop 0
	v_add_f32_e32 v24, v140, v28
	v_add_f32_e32 v28, v24, v29
	v_mul_f32_e32 v24, 0xbfb8aa3b, v135
	v_exp_f32_e32 v24, v24
	s_nop 0
	v_add_f32_e32 v24, 1.0, v24
	v_rcp_f32_e32 v137, v24
	s_nop 0
	v_pk_mul_f32 v[24:25], v[136:137], v[26:27]
	s_nop 0
	v_add_f32_e32 v24, v141, v24
	v_add_f32_e32 v25, v24, v25
	v_or_b32_e32 v24, 16, v20
	v_cvt_pk_bf16_f32 v26, v21, v32
	v_cvt_pk_bf16_f32 v27, v28, v25
	v_ashrrev_i32_e32 v25, 31, v24
	v_lshlrev_b64 v[24:25], 11, v[24:25]
	v_lshl_add_u64 v[24:25], s[6:7], 0, v[24:25]
	v_lshl_add_u64 v[24:25], v[24:25], 0, v[22:23]
	global_store_dwordx2 v[24:25], v[26:27], off
	v_mul_f32_e32 v21, 0xbfb8aa3b, v128
	v_exp_f32_e32 v21, v21
	v_pk_add_f32 v[32:33], v[130:131], v[16:17]
	v_add_f32_e32 v21, 1.0, v21
	v_rcp_f32_e32 v128, v21
	v_mul_f32_e32 v21, 0xbfb8aa3b, v129
	v_exp_f32_e32 v21, v21
	s_waitcnt vmcnt(12)
; __device__ __forceinline__ float bf2f(unsigned b) { return __uint_as_float(b << 16); }
; __device__ __forceinline__ unsigned cvt_pk_bf16(float lo, float hi) { unsigned r; asm volatile("v_cvt_pk_bf16_f32 %0, %1, %2" : "=v"(r) : "v"(lo), "v"(hi)); return r; }
; __device__ __forceinline__ float sigmoid_fast(float x) { return __builtin_amdgcn_rcpf(1.0f + __expf(-x)); }
;     __device__ __forceinline__ void operator()(EPI_SIG) const {
;     ...
;             for (int m = 0; m < 4; ++m) { const int row = row0 + ai * 128 + m * 16; const bf16* prow = P + (((((size_t)u.pm * 16 + u.pn) * 2 + ai) * 4 + m) * 8 + (wr * 4 + wc)) * 1024 + (fq * 16 + fr) * 4;
;                 v2u pw[4];
; #pragma unroll
;                 for (int g = 0; g < 4; ++g) pw[g] = *(const v2u*)(prow + g * 256);
;                 f32x4 t = (f32x4){0.f, 0.f, 0.f, 0.f};
; #pragma unroll
;                 for (int bj = 0; bj < 2; ++bj)
; #pragma unroll
;                     for (int n = 0; n < 2; ++n) { const int g = 2 * bj + n; const f32x4 a = acc[ai][bj][m][n] + bv[g];
;                         t[0] += sigmoid_fast(a[0]) * bf2f(pw[g].x & 0xffffu); t[1] += sigmoid_fast(a[1]) * bf2f(pw[g].x >> 16);
;                         t[2] += sigmoid_fast(a[2]) * bf2f(pw[g].y & 0xffffu); t[3] += sigmoid_fast(a[3]) * bf2f(pw[g].y >> 16); }
;                 v2u w; w.x = cvt_pk_bf16(t[0], t[1]); w.y = cvt_pk_bf16(t[2], t[3]);
;                 *(v2u*)(T + (size_t)row * 1024 + oc) = w; }
	v_mov_b64_e32 v[28:29], v[208:209]
	v_mov_b64_e32 v[30:31], v[210:211]
	v_mov_b64_e32 v[24:25], v[212:213]
	v_mov_b64_e32 v[26:27], v[214:215]
	v_lshl_add_u64 v[214:215], v[172:173], 0, s[14:15]
	global_load_dwordx2 v[208:209], v[214:215], off
	global_load_dwordx2 v[210:211], v[214:215], off offset:512
	global_load_dwordx2 v[212:213], v[214:215], off offset:1024
	s_nop 0
	global_load_dwordx2 v[214:215], v[214:215], off offset:1536
	v_lshlrev_b32_e32 v134, 16, v28
	v_add_f32_e32 v21, 1.0, v21
	v_rcp_f32_e32 v130, v21
	v_mul_f32_e32 v21, 0xbfb8aa3b, v32
	v_exp_f32_e32 v21, v21
	v_lshlrev_b32_e32 v135, 16, v30
	v_add_f32_e32 v21, 1.0, v21
	v_rcp_f32_e32 v32, v21
	v_mul_f32_e32 v21, 0xbfb8aa3b, v33
	v_exp_f32_e32 v21, v21
	v_mul_f32_e32 v33, 0xbfb8aa3b, v125
	v_exp_f32_e32 v33, v33
	v_and_b32_e32 v125, 0xffff0000, v30
	v_add_f32_e32 v21, 1.0, v21
	v_rcp_f32_e32 v132, v21
	v_mul_f32_e32 v21, 0xbfb8aa3b, v124
	v_exp_f32_e32 v21, v21
	v_add_f32_e32 v33, 1.0, v33
	v_rcp_f32_e32 v131, v33
	v_and_b32_e32 v124, 0xffff0000, v28
	v_add_f32_e32 v21, 1.0, v21
	v_rcp_f32_e32 v129, v21
	v_pk_mul_f32 v[124:125], v[130:131], v[124:125]
	v_and_b32_e32 v30, 0xffff0000, v29
	v_add_f32_e32 v28, 0, v124
	v_pk_mul_f32 v[128:129], v[128:129], v[134:135]
	v_lshlrev_b32_e32 v124, 16, v29
	v_add_f32_e32 v21, 0, v128
	v_add_f32_e32 v128, v28, v125
	v_mul_f32_e32 v28, 0xbfb8aa3b, v126
	v_exp_f32_e32 v28, v28
	v_lshlrev_b32_e32 v125, 16, v31
	v_and_b32_e32 v31, 0xffff0000, v31
	v_add_f32_e32 v21, v21, v129
	v_add_f32_e32 v28, 1.0, v28
	v_rcp_f32_e32 v33, v28
	s_nop 0
	v_pk_mul_f32 v[32:33], v[32:33], v[124:125]
	s_nop 0
	v_add_f32_e32 v28, 0, v32
	v_add_f32_e32 v124, v28, v33
	v_mul_f32_e32 v28, 0xbfb8aa3b, v127
	v_exp_f32_e32 v28, v28
	s_nop 0
	v_add_f32_e32 v28, 1.0, v28
	v_rcp_f32_e32 v133, v28
	s_nop 0
	v_pk_mul_f32 v[28:29], v[132:133], v[30:31]
	s_nop 0
	v_add_f32_e32 v28, 0, v28
	v_add_f32_e32 v125, v28, v29
	v_pk_add_f32 v[28:29], v[122:123], v[8:9]
	v_pk_add_f32 v[30:31], v[120:121], v[6:7]
	v_mul_f32_e32 v29, 0xbfb8aa3b, v29
	v_exp_f32_e32 v29, v29
	v_mul_f32_e32 v31, 0xbfb8aa3b, v31
	v_exp_f32_e32 v31, v31
	v_mul_f32_e32 v30, 0xbfb8aa3b, v30
	v_add_f32_e32 v29, 1.0, v29
	v_rcp_f32_e32 v120, v29
	v_mul_f32_e32 v29, 0xbfb8aa3b, v116
	v_exp_f32_e32 v29, v29
	v_exp_f32_e32 v30, v30
	v_add_f32_e32 v31, 1.0, v31
	v_rcp_f32_e32 v32, v31
	v_add_f32_e32 v29, 1.0, v29
	v_rcp_f32_e32 v31, v29
	v_mul_f32_e32 v29, 0xbfb8aa3b, v117
	v_exp_f32_e32 v29, v29
	v_add_f32_e32 v30, 1.0, v30
	v_rcp_f32_e32 v30, v30
	v_lshlrev_b32_e32 v123, 16, v26
	v_add_f32_e32 v29, 1.0, v29
	v_lshlrev_b32_e32 v122, 16, v24
	v_rcp_f32_e32 v33, v29
	v_pk_mul_f32 v[30:31], v[30:31], v[122:123]
	v_mul_f32_e32 v28, 0xbfb8aa3b, v28
	v_add_f32_e32 v21, v21, v30
	v_add_f32_e32 v21, v21, v31
	v_and_b32_e32 v31, 0xffff0000, v26
	v_and_b32_e32 v30, 0xffff0000, v24
	v_pk_mul_f32 v[30:31], v[32:33], v[30:31]
	v_exp_f32_e32 v28, v28
	v_add_f32_e32 v24, v128, v30
	v_add_f32_e32 v32, v24, v31
	v_mul_f32_e32 v24, 0xbfb8aa3b, v118
	v_exp_f32_e32 v24, v24
	v_add_f32_e32 v28, 1.0, v28
	v_rcp_f32_e32 v28, v28
	v_lshlrev_b32_e32 v31, 16, v27
	v_add_f32_e32 v24, 1.0, v24
	v_rcp_f32_e32 v29, v24
	v_lshlrev_b32_e32 v30, 16, v25
	v_and_b32_e32 v27, 0xffff0000, v27
	v_and_b32_e32 v26, 0xffff0000, v25
	v_pk_mul_f32 v[28:29], v[28:29], v[30:31]
	s_nop 0
	v_add_f32_e32 v24, v124, v28
	v_add_f32_e32 v28, v24, v29
	v_mul_f32_e32 v24, 0xbfb8aa3b, v119
	v_exp_f32_e32 v24, v24
	s_nop 0
	v_add_f32_e32 v24, 1.0, v24
	v_rcp_f32_e32 v121, v24
	s_nop 0
	v_pk_mul_f32 v[24:25], v[120:121], v[26:27]
	s_nop 0
	v_add_f32_e32 v24, v125, v24
	v_add_f32_e32 v25, v24, v25
	v_or_b32_e32 v24, 32, v20
	v_cvt_pk_bf16_f32 v26, v21, v32
	v_cvt_pk_bf16_f32 v27, v28, v25
	v_ashrrev_i32_e32 v25, 31, v24
	v_lshlrev_b64 v[24:25], 11, v[24:25]
	v_lshl_add_u64 v[24:25], s[6:7], 0, v[24:25]
	v_lshl_add_u64 v[24:25], v[24:25], 0, v[22:23]
	global_store_dwordx2 v[24:25], v[26:27], off
	v_mul_f32_e32 v21, 0xbfb8aa3b, v112
	v_exp_f32_e32 v21, v21
	v_pk_add_f32 v[32:33], v[114:115], v[16:17]
	v_or_b32_e32 v20, 48, v20
	s_bitset1_b32 s44, 16
	v_add_f32_e32 v21, 1.0, v21
	v_rcp_f32_e32 v112, v21
	v_mul_f32_e32 v21, 0xbfb8aa3b, v113
	v_exp_f32_e32 v21, v21
	s_waitcnt vmcnt(12)
; __device__ __forceinline__ float bf2f(unsigned b) { return __uint_as_float(b << 16); }
; __device__ __forceinline__ unsigned cvt_pk_bf16(float lo, float hi) { unsigned r; asm volatile("v_cvt_pk_bf16_f32 %0, %1, %2" : "=v"(r) : "v"(lo), "v"(hi)); return r; }
; __device__ __forceinline__ float sigmoid_fast(float x) { return __builtin_amdgcn_rcpf(1.0f + __expf(-x)); }
;     __device__ __forceinline__ void operator()(EPI_SIG) const {
;     ...
;             for (int m = 0; m < 4; ++m) { const int row = row0 + ai * 128 + m * 16; const bf16* prow = P + (((((size_t)u.pm * 16 + u.pn) * 2 + ai) * 4 + m) * 8 + (wr * 4 + wc)) * 1024 + (fq * 16 + fr) * 4;
;                 v2u pw[4];
; #pragma unroll
;                 for (int g = 0; g < 4; ++g) pw[g] = *(const v2u*)(prow + g * 256);
;                 f32x4 t = (f32x4){0.f, 0.f, 0.f, 0.f};
; #pragma unroll
;                 for (int bj = 0; bj < 2; ++bj)
; #pragma unroll
;                     for (int n = 0; n < 2; ++n) { const int g = 2 * bj + n; const f32x4 a = acc[ai][bj][m][n] + bv[g];
;                         t[0] += sigmoid_fast(a[0]) * bf2f(pw[g].x & 0xffffu); t[1] += sigmoid_fast(a[1]) * bf2f(pw[g].x >> 16);
;                         t[2] += sigmoid_fast(a[2]) * bf2f(pw[g].y & 0xffffu); t[3] += sigmoid_fast(a[3]) * bf2f(pw[g].y >> 16); }
;                 v2u w; w.x = cvt_pk_bf16(t[0], t[1]); w.y = cvt_pk_bf16(t[2], t[3]);
;                 *(v2u*)(T + (size_t)row * 1024 + oc) = w; }
	v_mov_b64_e32 v[28:29], v[216:217]
	v_mov_b64_e32 v[30:31], v[218:219]
	v_mov_b64_e32 v[24:25], v[220:221]
	v_mov_b64_e32 v[26:27], v[222:223]
	v_lshl_add_u64 v[222:223], v[174:175], 0, s[14:15]
	global_load_dwordx2 v[216:217], v[222:223], off
	global_load_dwordx2 v[218:219], v[222:223], off offset:512
	global_load_dwordx2 v[220:221], v[222:223], off offset:1024
	s_nop 0
	global_load_dwordx2 v[222:223], v[222:223], off offset:1536
	v_lshlrev_b32_e32 v118, 16, v28
	v_add_f32_e32 v21, 1.0, v21
	v_rcp_f32_e32 v114, v21
	v_mul_f32_e32 v21, 0xbfb8aa3b, v32
	v_exp_f32_e32 v21, v21
	v_lshlrev_b32_e32 v119, 16, v30
	v_add_f32_e32 v21, 1.0, v21
	v_rcp_f32_e32 v32, v21
	v_mul_f32_e32 v21, 0xbfb8aa3b, v33
	v_exp_f32_e32 v21, v21
	v_mul_f32_e32 v33, 0xbfb8aa3b, v109
	v_exp_f32_e32 v33, v33
	v_and_b32_e32 v109, 0xffff0000, v30
	v_add_f32_e32 v21, 1.0, v21
	v_rcp_f32_e32 v116, v21
	v_mul_f32_e32 v21, 0xbfb8aa3b, v108
	v_exp_f32_e32 v21, v21
	v_add_f32_e32 v33, 1.0, v33
	v_rcp_f32_e32 v115, v33
	v_and_b32_e32 v108, 0xffff0000, v28
	v_add_f32_e32 v21, 1.0, v21
	v_rcp_f32_e32 v113, v21
	v_pk_mul_f32 v[108:109], v[114:115], v[108:109]
	v_and_b32_e32 v30, 0xffff0000, v29
	v_add_f32_e32 v28, 0, v108
	v_pk_mul_f32 v[112:113], v[112:113], v[118:119]
	v_lshlrev_b32_e32 v108, 16, v29
	v_add_f32_e32 v21, 0, v112
	v_add_f32_e32 v112, v28, v109
	v_mul_f32_e32 v28, 0xbfb8aa3b, v110
	v_exp_f32_e32 v28, v28
	v_lshlrev_b32_e32 v109, 16, v31
	v_and_b32_e32 v31, 0xffff0000, v31
	v_add_f32_e32 v21, v21, v113
	v_add_f32_e32 v28, 1.0, v28
	v_rcp_f32_e32 v33, v28
	s_nop 0
	v_pk_mul_f32 v[32:33], v[32:33], v[108:109]
	s_nop 0
	v_add_f32_e32 v28, 0, v32
	v_add_f32_e32 v108, v28, v33
	v_mul_f32_e32 v28, 0xbfb8aa3b, v111
	v_exp_f32_e32 v28, v28
	s_nop 0
	v_add_f32_e32 v28, 1.0, v28
	v_rcp_f32_e32 v117, v28
	s_nop 0
	v_pk_mul_f32 v[28:29], v[116:117], v[30:31]
	s_nop 0
	v_add_f32_e32 v28, 0, v28
	v_add_f32_e32 v109, v28, v29
	v_pk_add_f32 v[28:29], v[106:107], v[8:9]
	v_pk_add_f32 v[30:31], v[104:105], v[6:7]
	v_mul_f32_e32 v29, 0xbfb8aa3b, v29
	v_exp_f32_e32 v29, v29
	v_mul_f32_e32 v31, 0xbfb8aa3b, v31
	v_exp_f32_e32 v31, v31
	v_mul_f32_e32 v30, 0xbfb8aa3b, v30
	v_add_f32_e32 v29, 1.0, v29
	v_rcp_f32_e32 v104, v29
	v_mul_f32_e32 v29, 0xbfb8aa3b, v100
	v_exp_f32_e32 v29, v29
	v_exp_f32_e32 v30, v30
	v_add_f32_e32 v31, 1.0, v31
	v_rcp_f32_e32 v32, v31
	v_add_f32_e32 v29, 1.0, v29
	v_rcp_f32_e32 v31, v29
	v_mul_f32_e32 v29, 0xbfb8aa3b, v101
	v_exp_f32_e32 v29, v29
	v_add_f32_e32 v30, 1.0, v30
	v_rcp_f32_e32 v30, v30
	v_lshlrev_b32_e32 v107, 16, v26
	v_add_f32_e32 v29, 1.0, v29
	v_lshlrev_b32_e32 v106, 16, v24
	v_rcp_f32_e32 v33, v29
	v_pk_mul_f32 v[30:31], v[30:31], v[106:107]
	v_mul_f32_e32 v28, 0xbfb8aa3b, v28
	v_add_f32_e32 v21, v21, v30
	v_add_f32_e32 v21, v21, v31
	v_and_b32_e32 v31, 0xffff0000, v26
	v_and_b32_e32 v30, 0xffff0000, v24
	v_pk_mul_f32 v[30:31], v[32:33], v[30:31]
	v_exp_f32_e32 v28, v28
	v_add_f32_e32 v24, v112, v30
	v_add_f32_e32 v32, v24, v31
	v_mul_f32_e32 v24, 0xbfb8aa3b, v102
	v_exp_f32_e32 v24, v24
	v_add_f32_e32 v28, 1.0, v28
	v_rcp_f32_e32 v28, v28
	v_lshlrev_b32_e32 v31, 16, v27
	v_add_f32_e32 v24, 1.0, v24
	v_rcp_f32_e32 v29, v24
	v_lshlrev_b32_e32 v30, 16, v25
	v_and_b32_e32 v27, 0xffff0000, v27
	v_and_b32_e32 v26, 0xffff0000, v25
	v_pk_mul_f32 v[28:29], v[28:29], v[30:31]
	v_pk_add_f32 v[30:31], v[96:97], v[14:15]
	v_add_f32_e32 v24, v108, v28
	v_add_f32_e32 v28, v24, v29
	v_mul_f32_e32 v24, 0xbfb8aa3b, v103
	v_exp_f32_e32 v24, v24
	v_mul_f32_e32 v30, 0xbfb8aa3b, v30
	v_mul_f32_e32 v31, 0xbfb8aa3b, v31
	v_exp_f32_e32 v30, v30
	v_add_f32_e32 v24, 1.0, v24
	v_rcp_f32_e32 v105, v24
	v_exp_f32_e32 v31, v31
	v_add_f32_e32 v30, 1.0, v30
	v_rcp_f32_e32 v30, v30
	v_pk_mul_f32 v[24:25], v[104:105], v[26:27]
	v_add_f32_e32 v31, 1.0, v31
	v_add_f32_e32 v24, v109, v24
	v_add_f32_e32 v25, v24, v25
	v_cvt_pk_bf16_f32 v24, v21, v32
	v_ashrrev_i32_e32 v21, 31, v20
	v_lshlrev_b64 v[20:21], 11, v[20:21]
	v_lshl_add_u64 v[20:21], s[6:7], 0, v[20:21]
	v_lshl_add_u64 v[20:21], v[20:21], 0, v[22:23]
	v_cvt_pk_bf16_f32 v25, v28, v25
	global_store_dwordx2 v[20:21], v[24:25], off
	v_pk_add_f32 v[28:29], v[98:99], v[16:17]
	v_rcp_f32_e32 v32, v31
	v_mul_f32_e32 v29, 0xbfb8aa3b, v29
	v_exp_f32_e32 v29, v29
	v_mul_f32_e32 v28, 0xbfb8aa3b, v28
	v_exp_f32_e32 v28, v28
	v_add_f32_e32 v29, 1.0, v29
	v_rcp_f32_e32 v96, v29
	v_mul_f32_e32 v29, 0xbfb8aa3b, v92
	v_exp_f32_e32 v29, v29
	v_add_f32_e32 v28, 1.0, v28
	v_rcp_f32_e32 v28, v28
	v_add_f32_e32 v29, 1.0, v29
	v_rcp_f32_e32 v31, v29
	s_waitcnt vmcnt(12)
; __device__ __forceinline__ float bf2f(unsigned b) { return __uint_as_float(b << 16); }
; __device__ __forceinline__ unsigned cvt_pk_bf16(float lo, float hi) { unsigned r; asm volatile("v_cvt_pk_bf16_f32 %0, %1, %2" : "=v"(r) : "v"(lo), "v"(hi)); return r; }
; __device__ __forceinline__ float sigmoid_fast(float x) { return __builtin_amdgcn_rcpf(1.0f + __expf(-x)); }
;     __device__ __forceinline__ void operator()(EPI_SIG) const {
;     ...
;             for (int m = 0; m < 4; ++m) { const int row = row0 + ai * 128 + m * 16; const bf16* prow = P + (((((size_t)u.pm * 16 + u.pn) * 2 + ai) * 4 + m) * 8 + (wr * 4 + wc)) * 1024 + (fq * 16 + fr) * 4;
;                 v2u pw[4];
; #pragma unroll
;                 for (int g = 0; g < 4; ++g) pw[g] = *(const v2u*)(prow + g * 256);
;                 f32x4 t = (f32x4){0.f, 0.f, 0.f, 0.f};
; #pragma unroll
;                 for (int bj = 0; bj < 2; ++bj)
; #pragma unroll
;                     for (int n = 0; n < 2; ++n) { const int g = 2 * bj + n; const f32x4 a = acc[ai][bj][m][n] + bv[g];
;                         t[0] += sigmoid_fast(a[0]) * bf2f(pw[g].x & 0xffffu); t[1] += sigmoid_fast(a[1]) * bf2f(pw[g].x >> 16);
;                         t[2] += sigmoid_fast(a[2]) * bf2f(pw[g].y & 0xffffu); t[3] += sigmoid_fast(a[3]) * bf2f(pw[g].y >> 16); }
;                 v2u w; w.x = cvt_pk_bf16(t[0], t[1]); w.y = cvt_pk_bf16(t[2], t[3]);
;                 *(v2u*)(T + (size_t)row * 1024 + oc) = w; }
	v_mov_b64_e32 v[24:25], v[242:243]
	v_mov_b64_e32 v[26:27], v[244:245]
	v_mov_b64_e32 v[20:21], v[246:247]
	v_mov_b64_e32 v[22:23], v[248:249]
	v_lshlrev_b32_e32 v98, 16, v24
	v_lshlrev_b32_e32 v99, 16, v26
	v_pk_mul_f32 v[30:31], v[30:31], v[98:99]
	s_nop 0
	v_add_f32_e32 v29, 0, v30
	v_add_f32_e32 v92, v29, v31
	v_mul_f32_e32 v29, 0xbfb8aa3b, v93
	v_exp_f32_e32 v29, v29
	v_and_b32_e32 v31, 0xffff0000, v26
	v_and_b32_e32 v30, 0xffff0000, v24
	v_and_b32_e32 v26, 0xffff0000, v25
	v_add_f32_e32 v29, 1.0, v29
	v_rcp_f32_e32 v33, v29
	s_nop 0
	v_pk_mul_f32 v[30:31], v[32:33], v[30:31]
	s_nop 0
	v_add_f32_e32 v24, 0, v30
	v_add_f32_e32 v93, v24, v31
	v_mul_f32_e32 v24, 0xbfb8aa3b, v94
	v_exp_f32_e32 v24, v24
	v_lshlrev_b32_e32 v31, 16, v27
	v_lshlrev_b32_e32 v30, 16, v25
	v_and_b32_e32 v27, 0xffff0000, v27
	v_add_f32_e32 v24, 1.0, v24
	v_rcp_f32_e32 v29, v24
	v_pk_add_f32 v[32:33], v[86:87], v[4:5]
	v_lshlrev_b32_e32 v87, 16, v22
	v_lshlrev_b32_e32 v86, 16, v20
	v_pk_mul_f32 v[28:29], v[28:29], v[30:31]
	s_nop 0
	v_add_f32_e32 v24, 0, v28
	v_add_f32_e32 v31, v24, v29
	v_mul_f32_e32 v24, 0xbfb8aa3b, v95
	v_exp_f32_e32 v24, v24
	s_nop 0
	v_add_f32_e32 v24, 1.0, v24
	v_rcp_f32_e32 v97, v24
	s_nop 0
	v_pk_mul_f32 v[24:25], v[96:97], v[26:27]
	s_nop 0
	v_add_f32_e32 v24, 0, v24
	v_add_f32_e32 v94, v24, v25
	v_pk_add_f32 v[24:25], v[90:91], v[8:9]
	v_pk_add_f32 v[26:27], v[88:89], v[6:7]
	v_mul_f32_e32 v25, 0xbfb8aa3b, v25
	v_exp_f32_e32 v25, v25
	v_mul_f32_e32 v26, 0xbfb8aa3b, v26
	v_mul_f32_e32 v27, 0xbfb8aa3b, v27
	v_exp_f32_e32 v26, v26
	v_add_f32_e32 v25, 1.0, v25
	v_rcp_f32_e32 v30, v25
	v_mul_f32_e32 v25, 0xbfb8aa3b, v84
	v_exp_f32_e32 v27, v27
	v_exp_f32_e32 v25, v25
	v_add_f32_e32 v26, 1.0, v26
	v_rcp_f32_e32 v26, v26
	v_add_f32_e32 v27, 1.0, v27
	v_add_f32_e32 v25, 1.0, v25
	v_rcp_f32_e32 v28, v27
	v_rcp_f32_e32 v27, v25
	v_mul_f32_e32 v24, 0xbfb8aa3b, v24
	v_exp_f32_e32 v24, v24
	v_pk_mul_f32 v[26:27], v[26:27], v[86:87]
	s_nop 0
	v_add_f32_e32 v25, v92, v26
	v_add_f32_e32 v84, v25, v27
	v_mul_f32_e32 v25, 0xbfb8aa3b, v85
	v_exp_f32_e32 v25, v25
	v_and_b32_e32 v27, 0xffff0000, v22
	v_and_b32_e32 v26, 0xffff0000, v20
	v_add_f32_e32 v24, 1.0, v24
	v_add_f32_e32 v25, 1.0, v25
	v_rcp_f32_e32 v29, v25
	v_rcp_f32_e32 v24, v24
	v_and_b32_e32 v22, 0xffff0000, v21
	v_pk_mul_f32 v[26:27], v[28:29], v[26:27]
	s_nop 0
	v_add_f32_e32 v20, v93, v26
	v_add_f32_e32 v28, v20, v27
	v_mul_f32_e32 v20, 0xbfb8aa3b, v32
	v_exp_f32_e32 v20, v20
	v_lshlrev_b32_e32 v27, 16, v23
	v_lshlrev_b32_e32 v26, 16, v21
	v_and_b32_e32 v23, 0xffff0000, v23
	v_add_f32_e32 v20, 1.0, v20
	v_rcp_f32_e32 v25, v20
	s_nop 0
	v_pk_mul_f32 v[24:25], v[24:25], v[26:27]
	s_nop 0
	v_add_f32_e32 v20, v31, v24
	v_add_f32_e32 v24, v20, v25
	v_mul_f32_e32 v20, 0xbfb8aa3b, v33
	v_exp_f32_e32 v20, v20
	s_nop 0
	v_add_f32_e32 v20, 1.0, v20
	v_rcp_f32_e32 v31, v20
	s_nop 0
	v_pk_mul_f32 v[20:21], v[30:31], v[22:23]
	s_nop 0
	v_add_f32_e32 v20, v94, v20
	v_add_co_u32_e32 v22, vcc, s2, v18
	v_add_f32_e32 v21, v20, v21
	s_nop 0
	v_addc_co_u32_e32 v23, vcc, 0, v19, vcc
	v_cvt_pk_bf16_f32 v20, v84, v28
	v_cvt_pk_bf16_f32 v21, v24, v21
	global_store_dwordx2 v[22:23], v[20:21], off
	v_pk_add_f32 v[28:29], v[82:83], v[16:17]
	v_pk_add_f32 v[30:31], v[80:81], v[14:15]
	v_mul_f32_e32 v29, 0xbfb8aa3b, v29
	v_exp_f32_e32 v29, v29
	v_mul_f32_e32 v30, 0xbfb8aa3b, v30
	v_mul_f32_e32 v31, 0xbfb8aa3b, v31
	v_exp_f32_e32 v30, v30
	v_add_f32_e32 v29, 1.0, v29
	v_rcp_f32_e32 v80, v29
	v_mul_f32_e32 v29, 0xbfb8aa3b, v76
	v_exp_f32_e32 v31, v31
	v_exp_f32_e32 v29, v29
	v_add_f32_e32 v30, 1.0, v30
	v_rcp_f32_e32 v30, v30
	v_add_f32_e32 v31, 1.0, v31
	v_add_f32_e32 v29, 1.0, v29
	v_rcp_f32_e32 v32, v31
	v_rcp_f32_e32 v31, v29
	v_mul_f32_e32 v28, 0xbfb8aa3b, v28
	v_exp_f32_e32 v28, v28
	s_mov_b32 s2, 0x48000
	v_add_f32_e32 v28, 1.0, v28
	v_rcp_f32_e32 v28, v28
	s_waitcnt vmcnt(8)
	v_mov_b64_e32 v[24:25], v[200:201]
	v_mov_b64_e32 v[26:27], v[202:203]
	v_mov_b64_e32 v[20:21], v[204:205]
	v_mov_b64_e32 v[22:23], v[206:207]
	v_lshlrev_b32_e32 v82, 16, v24
	v_lshlrev_b32_e32 v83, 16, v26
	v_pk_mul_f32 v[30:31], v[30:31], v[82:83]
	s_nop 0
	v_add_f32_e32 v29, 0, v30
	v_add_f32_e32 v76, v29, v31
	v_mul_f32_e32 v29, 0xbfb8aa3b, v77
	v_exp_f32_e32 v29, v29
	v_and_b32_e32 v31, 0xffff0000, v26
	v_and_b32_e32 v30, 0xffff0000, v24
	v_and_b32_e32 v26, 0xffff0000, v25
	v_add_f32_e32 v29, 1.0, v29
	v_rcp_f32_e32 v33, v29
	s_nop 0
	v_pk_mul_f32 v[30:31], v[32:33], v[30:31]
	s_nop 0
	v_add_f32_e32 v24, 0, v30
	v_add_f32_e32 v77, v24, v31
	v_mul_f32_e32 v24, 0xbfb8aa3b, v78
	v_exp_f32_e32 v24, v24
	v_lshlrev_b32_e32 v31, 16, v27
	v_lshlrev_b32_e32 v30, 16, v25
	v_and_b32_e32 v27, 0xffff0000, v27
	v_add_f32_e32 v24, 1.0, v24
	v_rcp_f32_e32 v29, v24
	v_pk_add_f32 v[32:33], v[70:71], v[4:5]
	v_lshlrev_b32_e32 v71, 16, v22
	v_lshlrev_b32_e32 v70, 16, v20
	v_pk_mul_f32 v[28:29], v[28:29], v[30:31]
	s_nop 0
	v_add_f32_e32 v24, 0, v28
	v_add_f32_e32 v31, v24, v29
	v_mul_f32_e32 v24, 0xbfb8aa3b, v79
	v_exp_f32_e32 v24, v24
	s_nop 0
	v_add_f32_e32 v24, 1.0, v24
	v_rcp_f32_e32 v81, v24
	s_nop 0
	v_pk_mul_f32 v[24:25], v[80:81], v[26:27]
	s_nop 0
	v_add_f32_e32 v24, 0, v24
	v_add_f32_e32 v78, v24, v25
	v_pk_add_f32 v[24:25], v[74:75], v[8:9]
	v_pk_add_f32 v[26:27], v[72:73], v[6:7]
	v_mul_f32_e32 v25, 0xbfb8aa3b, v25
	v_exp_f32_e32 v25, v25
	v_mul_f32_e32 v26, 0xbfb8aa3b, v26
	v_mul_f32_e32 v27, 0xbfb8aa3b, v27
	v_exp_f32_e32 v26, v26
	v_add_f32_e32 v25, 1.0, v25
	v_rcp_f32_e32 v30, v25
	v_mul_f32_e32 v25, 0xbfb8aa3b, v68
	v_exp_f32_e32 v27, v27
	v_exp_f32_e32 v25, v25
	v_add_f32_e32 v26, 1.0, v26
	v_rcp_f32_e32 v26, v26
	v_add_f32_e32 v27, 1.0, v27
; __device__ __forceinline__ float bf2f(unsigned b) { return __uint_as_float(b << 16); }
; __device__ __forceinline__ unsigned cvt_pk_bf16(float lo, float hi) { unsigned r; asm volatile("v_cvt_pk_bf16_f32 %0, %1, %2" : "=v"(r) : "v"(lo), "v"(hi)); return r; }
; __device__ __forceinline__ float sigmoid_fast(float x) { return __builtin_amdgcn_rcpf(1.0f + __expf(-x)); }
;     __device__ __forceinline__ void operator()(EPI_SIG) const {
;     ...
;             for (int m = 0; m < 4; ++m) { const int row = row0 + ai * 128 + m * 16; const bf16* prow = P + (((((size_t)u.pm * 16 + u.pn) * 2 + ai) * 4 + m) * 8 + (wr * 4 + wc)) * 1024 + (fq * 16 + fr) * 4;
;                 v2u pw[4];
; #pragma unroll
;                 for (int g = 0; g < 4; ++g) pw[g] = *(const v2u*)(prow + g * 256);
;                 f32x4 t = (f32x4){0.f, 0.f, 0.f, 0.f};
; #pragma unroll
;                 for (int bj = 0; bj < 2; ++bj)
; #pragma unroll
;                     for (int n = 0; n < 2; ++n) { const int g = 2 * bj + n; const f32x4 a = acc[ai][bj][m][n] + bv[g];
;                         t[0] += sigmoid_fast(a[0]) * bf2f(pw[g].x & 0xffffu); t[1] += sigmoid_fast(a[1]) * bf2f(pw[g].x >> 16);
;                         t[2] += sigmoid_fast(a[2]) * bf2f(pw[g].y & 0xffffu); t[3] += sigmoid_fast(a[3]) * bf2f(pw[g].y >> 16); }
;                 v2u w; w.x = cvt_pk_bf16(t[0], t[1]); w.y = cvt_pk_bf16(t[2], t[3]);
;                 *(v2u*)(T + (size_t)row * 1024 + oc) = w; }
	v_add_f32_e32 v25, 1.0, v25
	v_rcp_f32_e32 v28, v27
	v_rcp_f32_e32 v27, v25
	v_mul_f32_e32 v24, 0xbfb8aa3b, v24
	v_exp_f32_e32 v24, v24
	v_pk_mul_f32 v[26:27], v[26:27], v[70:71]
	s_nop 0
	v_add_f32_e32 v25, v76, v26
	v_add_f32_e32 v68, v25, v27
	v_mul_f32_e32 v25, 0xbfb8aa3b, v69
	v_exp_f32_e32 v25, v25
	v_and_b32_e32 v27, 0xffff0000, v22
	v_and_b32_e32 v26, 0xffff0000, v20
	v_add_f32_e32 v24, 1.0, v24
	v_add_f32_e32 v25, 1.0, v25
	v_rcp_f32_e32 v29, v25
	v_rcp_f32_e32 v24, v24
	v_and_b32_e32 v22, 0xffff0000, v21
	v_pk_mul_f32 v[26:27], v[28:29], v[26:27]
	s_nop 0
	v_add_f32_e32 v20, v77, v26
	v_add_f32_e32 v28, v20, v27
	v_mul_f32_e32 v20, 0xbfb8aa3b, v32
	v_exp_f32_e32 v20, v20
	v_lshlrev_b32_e32 v27, 16, v23
	v_lshlrev_b32_e32 v26, 16, v21
	v_and_b32_e32 v23, 0xffff0000, v23
	v_add_f32_e32 v20, 1.0, v20
	v_rcp_f32_e32 v25, v20
	s_nop 0
	v_pk_mul_f32 v[24:25], v[24:25], v[26:27]
	s_nop 0
	v_add_f32_e32 v20, v31, v24
	v_add_f32_e32 v24, v20, v25
	v_mul_f32_e32 v20, 0xbfb8aa3b, v33
	v_exp_f32_e32 v20, v20
	s_nop 0
	v_add_f32_e32 v20, 1.0, v20
	v_rcp_f32_e32 v31, v20
	s_nop 0
	v_pk_mul_f32 v[20:21], v[30:31], v[22:23]
	s_nop 0
	v_add_f32_e32 v20, v78, v20
	v_add_co_u32_e32 v22, vcc, s2, v18
	v_add_f32_e32 v21, v20, v21
	s_nop 0
	v_addc_co_u32_e32 v23, vcc, 0, v19, vcc
	v_cvt_pk_bf16_f32 v20, v68, v28
	v_cvt_pk_bf16_f32 v21, v24, v21
	global_store_dwordx2 v[22:23], v[20:21], off
	v_pk_add_f32 v[28:29], v[66:67], v[16:17]
	v_pk_add_f32 v[30:31], v[64:65], v[14:15]
	v_mul_f32_e32 v29, 0xbfb8aa3b, v29
	v_exp_f32_e32 v29, v29
	v_mul_f32_e32 v30, 0xbfb8aa3b, v30
	v_mul_f32_e32 v31, 0xbfb8aa3b, v31
	v_exp_f32_e32 v30, v30
	v_add_f32_e32 v29, 1.0, v29
	v_rcp_f32_e32 v64, v29
	v_mul_f32_e32 v29, 0xbfb8aa3b, v60
	v_exp_f32_e32 v31, v31
	v_exp_f32_e32 v29, v29
	v_add_f32_e32 v30, 1.0, v30
	v_rcp_f32_e32 v30, v30
	v_add_f32_e32 v31, 1.0, v31
	v_add_f32_e32 v29, 1.0, v29
	v_rcp_f32_e32 v32, v31
	v_rcp_f32_e32 v31, v29
	v_mul_f32_e32 v28, 0xbfb8aa3b, v28
	v_exp_f32_e32 v28, v28
	s_mov_b32 s2, 0x50000
	v_pk_add_f32 v[14:15], v[46:47], v[14:15]
	v_pk_add_f32 v[16:17], v[48:49], v[16:17]
	v_add_f32_e32 v28, 1.0, v28
	v_rcp_f32_e32 v28, v28
	v_mul_f32_e32 v15, 0xbfb8aa3b, v15
	v_exp_f32_e32 v15, v15
	v_mul_f32_e32 v14, 0xbfb8aa3b, v14
	v_exp_f32_e32 v14, v14
	v_add_f32_e32 v15, 1.0, v15
	v_add_f32_e32 v14, 1.0, v14
	v_rcp_f32_e32 v14, v14
	s_waitcnt vmcnt(4)
	v_mov_b64_e32 v[24:25], v[208:209]
	v_mov_b64_e32 v[26:27], v[210:211]
	v_mov_b64_e32 v[20:21], v[212:213]
	v_mov_b64_e32 v[22:23], v[214:215]
	v_lshlrev_b32_e32 v66, 16, v24
	v_lshlrev_b32_e32 v67, 16, v26
	v_pk_mul_f32 v[30:31], v[30:31], v[66:67]
	s_nop 0
	v_add_f32_e32 v29, 0, v30
	v_add_f32_e32 v60, v29, v31
	v_mul_f32_e32 v29, 0xbfb8aa3b, v61
	v_exp_f32_e32 v29, v29
	v_and_b32_e32 v31, 0xffff0000, v26
	v_and_b32_e32 v30, 0xffff0000, v24
	v_and_b32_e32 v26, 0xffff0000, v25
	v_add_f32_e32 v29, 1.0, v29
	v_rcp_f32_e32 v33, v29
	s_nop 0
	v_pk_mul_f32 v[30:31], v[32:33], v[30:31]
	s_nop 0
	v_add_f32_e32 v24, 0, v30
	v_add_f32_e32 v61, v24, v31
	v_mul_f32_e32 v24, 0xbfb8aa3b, v62
	v_exp_f32_e32 v24, v24
	v_lshlrev_b32_e32 v31, 16, v27
	v_lshlrev_b32_e32 v30, 16, v25
	v_and_b32_e32 v27, 0xffff0000, v27
	v_add_f32_e32 v24, 1.0, v24
	v_rcp_f32_e32 v29, v24
	v_pk_add_f32 v[32:33], v[54:55], v[4:5]
	v_lshlrev_b32_e32 v55, 16, v22
	v_lshlrev_b32_e32 v54, 16, v20
	v_pk_mul_f32 v[28:29], v[28:29], v[30:31]
	v_pk_add_f32 v[4:5], v[36:37], v[4:5]
	v_add_f32_e32 v24, 0, v28
	v_add_f32_e32 v31, v24, v29
	v_mul_f32_e32 v24, 0xbfb8aa3b, v63
	v_exp_f32_e32 v24, v24
	s_nop 0
	v_add_f32_e32 v24, 1.0, v24
	v_rcp_f32_e32 v65, v24
	s_nop 0
	v_pk_mul_f32 v[24:25], v[64:65], v[26:27]
	s_nop 0
	v_add_f32_e32 v24, 0, v24
	v_add_f32_e32 v62, v24, v25
	v_pk_add_f32 v[24:25], v[58:59], v[8:9]
	v_pk_add_f32 v[26:27], v[56:57], v[6:7]
	v_mul_f32_e32 v25, 0xbfb8aa3b, v25
	v_exp_f32_e32 v25, v25
	v_mul_f32_e32 v26, 0xbfb8aa3b, v26
	v_mul_f32_e32 v27, 0xbfb8aa3b, v27
	v_exp_f32_e32 v26, v26
	v_add_f32_e32 v25, 1.0, v25
	v_rcp_f32_e32 v30, v25
	v_mul_f32_e32 v25, 0xbfb8aa3b, v52
	v_exp_f32_e32 v27, v27
	v_exp_f32_e32 v25, v25
	v_add_f32_e32 v26, 1.0, v26
	v_rcp_f32_e32 v26, v26
	v_add_f32_e32 v27, 1.0, v27
	v_add_f32_e32 v25, 1.0, v25
	v_rcp_f32_e32 v28, v27
	v_rcp_f32_e32 v27, v25
	v_mul_f32_e32 v24, 0xbfb8aa3b, v24
	v_exp_f32_e32 v24, v24
	v_pk_add_f32 v[6:7], v[38:39], v[6:7]
	v_pk_mul_f32 v[26:27], v[26:27], v[54:55]
	v_mul_f32_e32 v7, 0xbfb8aa3b, v7
	v_add_f32_e32 v25, v60, v26
	v_add_f32_e32 v52, v25, v27
	v_mul_f32_e32 v25, 0xbfb8aa3b, v53
	v_exp_f32_e32 v25, v25
	v_and_b32_e32 v27, 0xffff0000, v22
	v_and_b32_e32 v26, 0xffff0000, v20
	v_add_f32_e32 v24, 1.0, v24
	v_add_f32_e32 v25, 1.0, v25
	v_rcp_f32_e32 v29, v25
	v_rcp_f32_e32 v24, v24
	v_and_b32_e32 v22, 0xffff0000, v21
	v_exp_f32_e32 v7, v7
	v_pk_mul_f32 v[26:27], v[28:29], v[26:27]
	v_pk_add_f32 v[8:9], v[40:41], v[8:9]
	v_add_f32_e32 v20, v61, v26
	v_add_f32_e32 v28, v20, v27
	v_mul_f32_e32 v20, 0xbfb8aa3b, v32
	v_exp_f32_e32 v20, v20
	v_lshlrev_b32_e32 v27, 16, v23
	v_lshlrev_b32_e32 v26, 16, v21
	v_and_b32_e32 v23, 0xffff0000, v23
	v_add_f32_e32 v20, 1.0, v20
	v_rcp_f32_e32 v25, v20
	v_add_f32_e32 v7, 1.0, v7
	v_mul_f32_e32 v6, 0xbfb8aa3b, v6
	v_exp_f32_e32 v6, v6
	v_pk_mul_f32 v[24:25], v[24:25], v[26:27]
	v_add_f32_e32 v6, 1.0, v6
	v_add_f32_e32 v20, v31, v24
	v_add_f32_e32 v24, v20, v25
	v_mul_f32_e32 v20, 0xbfb8aa3b, v33
	v_exp_f32_e32 v20, v20
	v_rcp_f32_e32 v6, v6
	v_add_f32_e32 v20, 1.0, v20
	v_rcp_f32_e32 v31, v20
	s_nop 0
	v_pk_mul_f32 v[20:21], v[30:31], v[22:23]
	s_nop 0
	v_add_f32_e32 v20, v62, v20
	v_add_co_u32_e32 v22, vcc, s2, v18
	v_add_f32_e32 v21, v20, v21
	s_nop 0
	v_addc_co_u32_e32 v23, vcc, 0, v19, vcc
	v_cvt_pk_bf16_f32 v20, v52, v28
	v_cvt_pk_bf16_f32 v21, v24, v21
	global_store_dwordx2 v[22:23], v[20:21], off
	v_rcp_f32_e32 v28, v15
	v_mul_f32_e32 v15, 0xbfb8aa3b, v16
	v_exp_f32_e32 v15, v15
	s_mov_b64 s[2:3], -1
	v_add_f32_e32 v15, 1.0, v15
	v_rcp_f32_e32 v16, v15
	v_mul_f32_e32 v15, 0xbfb8aa3b, v17
	v_exp_f32_e32 v15, v15
	s_waitcnt vmcnt(4)
; __device__ __forceinline__ float bf2f(unsigned b) { return __uint_as_float(b << 16); }
; __device__ __forceinline__ unsigned cvt_pk_bf16(float lo, float hi) { unsigned r; asm volatile("v_cvt_pk_bf16_f32 %0, %1, %2" : "=v"(r) : "v"(lo), "v"(hi)); return r; }
; __device__ __forceinline__ float sigmoid_fast(float x) { return __builtin_amdgcn_rcpf(1.0f + __expf(-x)); }
;     __device__ __forceinline__ void operator()(EPI_SIG) const {
;     ...
;             for (int m = 0; m < 4; ++m) { const int row = row0 + ai * 128 + m * 16; const bf16* prow = P + (((((size_t)u.pm * 16 + u.pn) * 2 + ai) * 4 + m) * 8 + (wr * 4 + wc)) * 1024 + (fq * 16 + fr) * 4;
;                 v2u pw[4];
; #pragma unroll
;                 for (int g = 0; g < 4; ++g) pw[g] = *(const v2u*)(prow + g * 256);
;                 f32x4 t = (f32x4){0.f, 0.f, 0.f, 0.f};
; #pragma unroll
;                 for (int bj = 0; bj < 2; ++bj)
; #pragma unroll
;                     for (int n = 0; n < 2; ++n) { const int g = 2 * bj + n; const f32x4 a = acc[ai][bj][m][n] + bv[g];
;                         t[0] += sigmoid_fast(a[0]) * bf2f(pw[g].x & 0xffffu); t[1] += sigmoid_fast(a[1]) * bf2f(pw[g].x >> 16);
;                         t[2] += sigmoid_fast(a[2]) * bf2f(pw[g].y & 0xffffu); t[3] += sigmoid_fast(a[3]) * bf2f(pw[g].y >> 16); }
;                 v2u w; w.x = cvt_pk_bf16(t[0], t[1]); w.y = cvt_pk_bf16(t[2], t[3]);
;                 *(v2u*)(T + (size_t)row * 1024 + oc) = w; }
	v_mov_b64_e32 v[24:25], v[216:217]
	v_mov_b64_e32 v[26:27], v[218:219]
	v_mov_b64_e32 v[20:21], v[220:221]
	v_mov_b64_e32 v[22:23], v[222:223]
	v_lshlrev_b32_e32 v32, 16, v24
	v_add_f32_e32 v15, 1.0, v15
	v_rcp_f32_e32 v30, v15
	v_rcp_f32_e32 v15, v10
	v_lshlrev_b32_e32 v33, 16, v26
	v_pk_mul_f32 v[14:15], v[14:15], v[32:33]
	s_nop 0
	v_add_f32_e32 v10, 0, v14
	v_add_f32_e32 v32, v10, v15
	v_mul_f32_e32 v10, 0xbfb8aa3b, v11
	v_exp_f32_e32 v10, v10
	v_and_b32_e32 v11, 0xffff0000, v26
	v_lshlrev_b32_e32 v15, 16, v22
	v_lshlrev_b32_e32 v14, 16, v20
	v_add_f32_e32 v10, 1.0, v10
	v_rcp_f32_e32 v29, v10
	v_and_b32_e32 v10, 0xffff0000, v24
	v_pk_mul_f32 v[10:11], v[28:29], v[10:11]
	s_nop 0
	v_add_f32_e32 v10, 0, v10
	v_add_f32_e32 v24, v10, v11
	v_mul_f32_e32 v10, 0xbfb8aa3b, v12
	v_exp_f32_e32 v10, v10
	v_lshlrev_b32_e32 v11, 16, v27
	v_add_f32_e32 v10, 1.0, v10
	v_rcp_f32_e32 v17, v10
	v_lshlrev_b32_e32 v10, 16, v25
	v_pk_mul_f32 v[10:11], v[16:17], v[10:11]
	s_nop 0
	v_add_f32_e32 v10, 0, v10
	v_add_f32_e32 v16, v10, v11
	v_mul_f32_e32 v10, 0xbfb8aa3b, v13
	v_exp_f32_e32 v10, v10
	v_and_b32_e32 v11, 0xffff0000, v27
	v_add_f32_e32 v10, 1.0, v10
	v_rcp_f32_e32 v31, v10
	v_and_b32_e32 v10, 0xffff0000, v25
	v_pk_mul_f32 v[10:11], v[30:31], v[10:11]
	s_nop 0
	v_add_f32_e32 v10, 0, v10
	v_add_f32_e32 v17, v10, v11
	v_rcp_f32_e32 v10, v7
	v_mul_f32_e32 v7, 0xbfb8aa3b, v8
	v_exp_f32_e32 v7, v7
	s_nop 0
	v_add_f32_e32 v7, 1.0, v7
	v_rcp_f32_e32 v8, v7
	v_mul_f32_e32 v7, 0xbfb8aa3b, v9
	v_exp_f32_e32 v7, v7
	s_nop 0
	v_add_f32_e32 v7, 1.0, v7
	v_rcp_f32_e32 v12, v7
	v_rcp_f32_e32 v7, v2
	s_nop 0
	v_pk_mul_f32 v[6:7], v[6:7], v[14:15]
	s_nop 0
	v_add_f32_e32 v2, v32, v6
	v_add_f32_e32 v6, v2, v7
	v_mul_f32_e32 v2, 0xbfb8aa3b, v3
	v_exp_f32_e32 v2, v2
	v_and_b32_e32 v3, 0xffff0000, v22
	v_add_f32_e32 v2, 1.0, v2
	v_rcp_f32_e32 v11, v2
	v_and_b32_e32 v2, 0xffff0000, v20
	v_pk_mul_f32 v[2:3], v[10:11], v[2:3]
	s_nop 0
	v_add_f32_e32 v2, v24, v2
	v_add_f32_e32 v7, v2, v3
	v_mul_f32_e32 v2, 0xbfb8aa3b, v4
	v_exp_f32_e32 v2, v2
	v_lshlrev_b32_e32 v3, 16, v23
	v_add_f32_e32 v2, 1.0, v2
	v_rcp_f32_e32 v9, v2
	v_lshlrev_b32_e32 v2, 16, v21
	v_pk_mul_f32 v[2:3], v[8:9], v[2:3]
	s_nop 0
	v_add_f32_e32 v2, v16, v2
	v_add_f32_e32 v4, v2, v3
	v_mul_f32_e32 v2, 0xbfb8aa3b, v5
	v_exp_f32_e32 v2, v2
	v_and_b32_e32 v3, 0xffff0000, v23
	v_add_f32_e32 v2, 1.0, v2
	v_rcp_f32_e32 v13, v2
	v_and_b32_e32 v2, 0xffff0000, v21
	v_pk_mul_f32 v[2:3], v[12:13], v[2:3]
	s_nop 0
	v_add_f32_e32 v2, v17, v2
	v_add_f32_e32 v3, v2, v3
	v_cvt_pk_bf16_f32 v2, v6, v7
	v_cvt_pk_bf16_f32 v3, v4, v3
	v_add_co_u32_e32 v4, vcc, 0x58000, v18
	s_nop 1
	v_addc_co_u32_e32 v5, vcc, 0, v19, vcc
	s_andn2_b64 vcc, exec, s[0:1]
	global_store_dwordx2 v[4:5], v[2:3], off
	s_cbranch_vccnz .LBB0_1852
	s_andn2_b64 vcc, exec, s[4:5]
	s_cbranch_vccnz .LBB0_1851
	s_barrier
	s_branch .LBB0_1851
